# LN residual L2-warming dummy loads + LN slot/gamma hoists + means batched loads + MODE0 sink scalar load
# baseline (speedup 1.0000x reference)
.LBB0_682:
	s_andn2_b64 vcc, exec, s[12:13]
	v_readlane_b32 s12, v253, 52
	v_readlane_b32 s13, v253, 53
	s_nop 1
	v_lshl_add_u64 v[196:197], v[186:187], 1, s[12:13]
	s_cbranch_vccnz .LBB0_684
	s_waitcnt vmcnt(0)
	v_lshlrev_b64 v[144:145], 11, v[188:189]
	v_ashrrev_i32_e32 v199, 31, v198
	v_lshl_add_u64 v[148:149], v[196:197], 0, v[144:145]
	v_lshlrev_b64 v[152:153], 11, v[198:199]
	global_load_dwordx4 v[144:147], v[148:149], off
	s_nop 0
	global_load_dwordx4 v[148:151], v[148:149], off offset:256
	v_lshl_add_u64 v[152:153], v[196:197], 0, v[152:153]
	global_load_dwordx4 v[160:163], v[152:153], off
	global_load_dwordx4 v[164:167], v[152:153], off offset:256
	v_add_u32_e32 v242, 32, v188
	v_ashrrev_i32_e32 v243, 31, v242
	v_lshlrev_b64 v[242:243], 11, v[242:243]
	v_lshl_add_u64 v[242:243], v[196:197], 0, v[242:243]
	global_load_dword v244, v[242:243], off
	global_load_dword v244, v[242:243], off offset:256
	v_add_u32_e32 v242, 48, v188
	v_ashrrev_i32_e32 v243, 31, v242
	v_lshlrev_b64 v[242:243], 11, v[242:243]
	v_lshl_add_u64 v[242:243], v[196:197], 0, v[242:243]
	global_load_dword v244, v[242:243], off
	global_load_dword v244, v[242:243], off offset:256
	v_add_u32_e32 v242, 128, v188
	v_ashrrev_i32_e32 v243, 31, v242
	v_lshlrev_b64 v[242:243], 11, v[242:243]
	v_lshl_add_u64 v[242:243], v[196:197], 0, v[242:243]
	global_load_dword v244, v[242:243], off
	global_load_dword v244, v[242:243], off offset:256
	v_add_u32_e32 v242, 144, v188
	v_ashrrev_i32_e32 v243, 31, v242
	v_lshlrev_b64 v[242:243], 11, v[242:243]
	v_lshl_add_u64 v[242:243], v[196:197], 0, v[242:243]
	global_load_dword v244, v[242:243], off
	global_load_dword v244, v[242:243], off offset:256
	v_add_u32_e32 v242, 160, v188
	v_ashrrev_i32_e32 v243, 31, v242
	v_lshlrev_b64 v[242:243], 11, v[242:243]
	v_lshl_add_u64 v[242:243], v[196:197], 0, v[242:243]
	global_load_dword v244, v[242:243], off
	global_load_dword v244, v[242:243], off offset:256
	v_add_u32_e32 v242, 176, v188
	v_ashrrev_i32_e32 v243, 31, v242
	v_lshlrev_b64 v[242:243], 11, v[242:243]
	v_lshl_add_u64 v[242:243], v[196:197], 0, v[242:243]
	global_load_dword v244, v[242:243], off
	global_load_dword v244, v[242:243], off offset:256
	s_waitcnt vmcnt(15)
	v_lshlrev_b32_e32 v152, 16, v144
	v_and_b32_e32 v153, 0xffff0000, v144
	v_lshlrev_b32_e32 v144, 16, v145
	v_and_b32_e32 v145, 0xffff0000, v145
	v_lshlrev_b32_e32 v154, 16, v146
	v_and_b32_e32 v155, 0xffff0000, v146
	s_waitcnt vmcnt(14)
	v_lshlrev_b32_e32 v168, 16, v150
	v_and_b32_e32 v169, 0xffff0000, v150
	v_lshlrev_b32_e32 v170, 16, v151
	v_and_b32_e32 v171, 0xffff0000, v151
	v_lshlrev_b32_e32 v146, 16, v147
	v_and_b32_e32 v147, 0xffff0000, v147
	v_lshlrev_b32_e32 v156, 16, v148
	v_and_b32_e32 v157, 0xffff0000, v148
	v_lshlrev_b32_e32 v158, 16, v149
	v_and_b32_e32 v159, 0xffff0000, v149
	v_pk_add_f32 v[150:151], v[144:145], 0 op_sel_hi:[1,0]
	v_pk_add_f32 v[148:149], v[152:153], 0 op_sel_hi:[1,0]
	v_pk_add_f32 v[144:145], v[154:155], 0 op_sel_hi:[1,0]
	v_pk_add_f32 v[154:155], v[170:171], 0 op_sel_hi:[1,0]
	v_pk_add_f32 v[152:153], v[168:169], 0 op_sel_hi:[1,0]
	s_waitcnt vmcnt(13)
	v_lshlrev_b32_e32 v168, 16, v160
	v_and_b32_e32 v169, 0xffff0000, v160
	v_lshlrev_b32_e32 v160, 16, v161
	v_and_b32_e32 v161, 0xffff0000, v161
	v_lshlrev_b32_e32 v170, 16, v162
	v_and_b32_e32 v171, 0xffff0000, v162
	v_lshlrev_b32_e32 v162, 16, v163
	v_and_b32_e32 v163, 0xffff0000, v163
	s_waitcnt vmcnt(12)
	v_lshlrev_b32_e32 v172, 16, v164
	v_and_b32_e32 v173, 0xffff0000, v164
	v_lshlrev_b32_e32 v174, 16, v165
	v_and_b32_e32 v175, 0xffff0000, v165
	v_lshlrev_b32_e32 v198, 16, v166
	v_and_b32_e32 v199, 0xffff0000, v166
	v_lshlrev_b32_e32 v200, 16, v167
	v_and_b32_e32 v201, 0xffff0000, v167
	v_pk_add_f32 v[146:147], v[146:147], 0 op_sel_hi:[1,0]
	v_pk_add_f32 v[158:159], v[158:159], 0 op_sel_hi:[1,0]
	v_pk_add_f32 v[156:157], v[156:157], 0 op_sel_hi:[1,0]
	v_pk_add_f32 v[166:167], v[160:161], 0 op_sel_hi:[1,0]
	v_pk_add_f32 v[164:165], v[168:169], 0 op_sel_hi:[1,0]
	v_pk_add_f32 v[162:163], v[162:163], 0 op_sel_hi:[1,0]
	v_pk_add_f32 v[160:161], v[170:171], 0 op_sel_hi:[1,0]
	v_pk_add_f32 v[174:175], v[174:175], 0 op_sel_hi:[1,0]
	v_pk_add_f32 v[172:173], v[172:173], 0 op_sel_hi:[1,0]
	v_pk_add_f32 v[170:171], v[200:201], 0 op_sel_hi:[1,0]
	v_pk_add_f32 v[168:169], v[198:199], 0 op_sel_hi:[1,0]
